# speedup vs baseline: 1.0101x; 1.0101x over previous
; template <int EPI>
; __device__ __forceinline__ void gemm_phase(char* shm, const u16* A, const u16* Bt, int K, int nM, int nN, u16* Cb, float* X,
;                            int ldc, const u16* G, float* SQ, int bid, int nb) {
;     ...
; #pragma unroll
;       for (int q = 0; q < 8; ++q) rs[q] = ((const float*)(shm + LDS_RST))[(q >> 2) * 128 + wr * 64 + (q & 3) * 16 + fr];
;     }
; #pragma unroll
;     for (int ai = 0; ai < 2; ++ai)
; #pragma unroll
;       for (int bj = 0; bj < 2; ++bj)
; #pragma unroll
;         for (int m = 0; m < 4; ++m) {
;           const long row = brow + ai * 128 + wr * 64 + m * 16 + fr;
;           const int col = bcol + bj * 128 + wc * 32 + fq * 8;
;           float c[8];
; #pragma unroll
;           for (int j = 0; j < 4; ++j) { c[j] = acc[ai][bj][m][0][j]; c[4 + j] = acc[ai][bj][m][1][j]; }
;           if (EPI == EPI_BF16) {
;             const float r1 = rs[ai * 4 + m];
;             u16x8 o;
; #pragma unroll
;             for (int j = 0; j < 8; ++j) o[j] = f2bf(c[j] * r1);
;             *(u16x8*)(Cb + row * ldc + col) = o;
.LBB0_387:
	v_and_b32_e32 v134, 15, v0
	v_lshlrev_b32_e32 v130, 2, v134
	s_movk_i32 s5, 0xff00
	v_and_or_b32 v130, v0, s5, v130
	v_add_u32_e32 v130, 0x24000, v130
	ds_read2_b32 v[138:139], v130 offset1:16
	ds_read2_b32 v[136:137], v130 offset0:32 offset1:48
	ds_read2_b32 v[132:133], v130 offset0:128 offset1:144
	ds_read2_b32 v[130:131], v130 offset0:160 offset1:176
	v_ashrrev_i32_e32 v135, 2, v0
	v_lshrrev_b32_e32 v0, 1, v0
	v_and_b32_e32 v135, 0xffffffc0, v135
	v_or_b32_e32 v134, s4, v134
	v_and_b32_e32 v0, 0x78, v0
	v_add_u32_e32 v140, v134, v135
	v_or_b32_e32 v134, s6, v0
	s_waitcnt lgkmcnt(0)
	v_mul_f32_e32 v0, v126, v138
	v_mov_b32_e32 v126, v127
	v_mov_b32_e32 v127, v128
	v_pk_mul_f32 v[126:127], v[126:127], v[138:139] op_sel_hi:[1,0]
	v_pk_mov_b32 v[128:129], v[128:129], v[122:123] op_sel:[1,0]
	v_mov_b32_e32 v122, v123
	v_mov_b32_e32 v123, v124
	v_cvt_pk_bf16_f32 v0, v0, s0
	v_cvt_pk_bf16_f32 v127, v126, v127
	v_pk_mul_f32 v[128:129], v[128:129], v[138:139] op_sel_hi:[1,0]
	v_pk_mul_f32 v[122:123], v[122:123], v[138:139] op_sel_hi:[1,0]
	v_perm_b32 v126, v127, v0, s74
	v_cvt_pk_bf16_f32 v0, v128, v129
	v_cvt_pk_bf16_f32 v122, v122, v123
	v_alignbit_b32 v127, v0, v127, 16
	v_alignbit_b32 v128, v122, v0, 16
	v_mul_f32_e32 v0, v125, v138
	v_cvt_pk_bf16_f32 v0, v0, s0
	v_alignbit_b32 v129, v0, v122, 16
	v_mul_f32_e32 v0, v118, v139
	v_cvt_pk_bf16_f32 v125, v0, s0
	v_mov_b32_e32 v118, v119
	v_mov_b32_e32 v119, v120
	v_mov_b32_e32 v0, v139
	v_pk_mov_b32 v[120:121], v[120:121], v[114:115] op_sel:[1,0]
	v_mov_b32_e32 v114, v115
	v_mov_b32_e32 v115, v116
	v_pk_mul_f32 v[114:115], v[114:115], v[0:1] op_sel_hi:[1,0]
	v_mul_f32_e32 v110, v110, v136
	v_cvt_pk_bf16_f32 v114, v114, v115
	v_mul_f32_e32 v115, v117, v139
	v_cvt_pk_bf16_f32 v117, v110, s0
	v_mov_b32_e32 v110, v111
	v_mov_b32_e32 v111, v112
	v_pk_mov_b32 v[112:113], v[112:113], v[106:107] op_sel:[1,0]
	v_mov_b32_e32 v106, v107
	v_mov_b32_e32 v107, v108
	v_pk_mul_f32 v[106:107], v[106:107], v[136:137] op_sel_hi:[1,0]
	v_ashrrev_i32_e32 v135, 31, v134
	v_pk_mul_f32 v[110:111], v[110:111], v[136:137] op_sel_hi:[1,0]
	v_pk_mul_f32 v[112:113], v[112:113], v[136:137] op_sel_hi:[1,0]
	v_cvt_pk_bf16_f32 v106, v106, v107
	v_mul_f32_e32 v107, v109, v136
	v_lshl_add_u64 v[134:135], v[134:135], 1, s[94:95]
	v_or_b32_e32 v116, 32, v140
	v_cvt_pk_bf16_f32 v111, v110, v111
	v_cvt_pk_bf16_f32 v112, v112, v113
	v_cvt_pk_bf16_f32 v107, v107, s0
	v_perm_b32 v110, v111, v117, s74
	v_alignbit_b32 v111, v112, v111, 16
	v_alignbit_b32 v112, v106, v112, 16
	v_alignbit_b32 v113, v107, v106, 16
	v_mad_i64_i32 v[106:107], s[4:5], v116, s66, v[134:135]
	v_mul_f32_e32 v102, v102, v137
	v_mul_f32_e32 v94, v94, v138
	global_store_dwordx4 v[106:107], v[110:113], off nt
	v_mul_f32_e32 v86, v86, v139
	v_pk_mul_f32 v[118:119], v[118:119], v[0:1] op_sel_hi:[1,0]
	v_cvt_pk_bf16_f32 v110, v102, s0
	v_mov_b32_e32 v102, v103
	v_mov_b32_e32 v103, v104
	v_pk_mov_b32 v[104:105], v[104:105], v[98:99] op_sel:[1,0]
	v_mov_b32_e32 v98, v99
	v_mov_b32_e32 v99, v100
	v_cvt_pk_bf16_f32 v100, v94, s0
	v_mov_b32_e32 v94, v95
	v_mov_b32_e32 v95, v96
	v_pk_mov_b32 v[96:97], v[96:97], v[90:91] op_sel:[1,0]
	v_mov_b32_e32 v90, v91
	v_mov_b32_e32 v91, v92
	v_pk_mul_f32 v[90:91], v[90:91], v[138:139] op_sel_hi:[1,0]
	v_pk_mul_f32 v[94:95], v[94:95], v[138:139] op_sel_hi:[1,0]
	v_pk_mul_f32 v[96:97], v[96:97], v[138:139] op_sel_hi:[1,0]
	v_cvt_pk_bf16_f32 v90, v90, v91
	v_mul_f32_e32 v91, v93, v138
	v_cvt_pk_bf16_f32 v95, v94, v95
	v_cvt_pk_bf16_f32 v96, v96, v97
	v_cvt_pk_bf16_f32 v91, v91, s0
	v_perm_b32 v94, v95, v100, s74
	v_alignbit_b32 v95, v96, v95, 16
	v_alignbit_b32 v96, v90, v96, 16
	v_alignbit_b32 v97, v91, v90, 16
	v_cvt_pk_bf16_f32 v90, v86, s0
	v_mov_b32_e32 v86, v87
	v_mov_b32_e32 v87, v88
	v_pk_mov_b32 v[88:89], v[88:89], v[82:83] op_sel:[1,0]
	v_mov_b32_e32 v82, v83
	v_mov_b32_e32 v83, v84
	v_pk_mul_f32 v[82:83], v[82:83], v[0:1] op_sel_hi:[1,0]
	v_pk_mul_f32 v[120:121], v[120:121], v[0:1] op_sel_hi:[1,0]
	v_pk_mul_f32 v[86:87], v[86:87], v[0:1] op_sel_hi:[1,0]
	v_pk_mul_f32 v[88:89], v[88:89], v[0:1] op_sel_hi:[1,0]
	v_cvt_pk_bf16_f32 v0, v82, v83
	v_mul_f32_e32 v82, v85, v139
	v_cvt_pk_bf16_f32 v87, v86, v87
	v_cvt_pk_bf16_f32 v88, v88, v89
	v_cvt_pk_bf16_f32 v82, v82, s0
	v_perm_b32 v86, v87, v90, s74
	v_alignbit_b32 v87, v88, v87, 16
	v_alignbit_b32 v88, v0, v88, 16
	v_alignbit_b32 v89, v82, v0, 16
	v_mul_f32_e32 v0, v78, v136
	v_mov_b32_e32 v78, v79
	v_mov_b32_e32 v79, v80
	v_pk_mul_f32 v[78:79], v[78:79], v[136:137] op_sel_hi:[1,0]
	v_pk_mov_b32 v[80:81], v[80:81], v[74:75] op_sel:[1,0]
	v_mov_b32_e32 v74, v75
	v_mov_b32_e32 v75, v76
	v_cvt_pk_bf16_f32 v0, v0, s0
	v_cvt_pk_bf16_f32 v79, v78, v79
	v_pk_mul_f32 v[80:81], v[80:81], v[136:137] op_sel_hi:[1,0]
	v_pk_mul_f32 v[74:75], v[74:75], v[136:137] op_sel_hi:[1,0]
	v_perm_b32 v78, v79, v0, s74
	v_cvt_pk_bf16_f32 v0, v80, v81
	v_cvt_pk_bf16_f32 v74, v74, v75
	v_alignbit_b32 v79, v0, v79, 16
	v_alignbit_b32 v80, v74, v0, 16
	v_mul_f32_e32 v0, v77, v136
	v_cvt_pk_bf16_f32 v0, v0, s0
	v_or_b32_e32 v109, 48, v140
	v_mov_b32_e32 v108, v137
	v_alignbit_b32 v81, v0, v74, 16
	v_mul_f32_e32 v0, v70, v137
	v_mov_b32_e32 v70, v71
	v_mov_b32_e32 v71, v72
	v_pk_mul_f32 v[70:71], v[70:71], v[108:109] op_sel_hi:[1,0]
	v_pk_mov_b32 v[72:73], v[72:73], v[66:67] op_sel:[1,0]
	v_mov_b32_e32 v66, v67
	v_mov_b32_e32 v67, v68
	v_cvt_pk_bf16_f32 v0, v0, s0
	v_cvt_pk_bf16_f32 v71, v70, v71
	v_pk_mul_f32 v[72:73], v[72:73], v[108:109] op_sel_hi:[1,0]
	v_pk_mul_f32 v[66:67], v[66:67], v[108:109] op_sel_hi:[1,0]
	v_perm_b32 v70, v71, v0, s74
	v_cvt_pk_bf16_f32 v0, v72, v73
	v_cvt_pk_bf16_f32 v66, v66, v67
; template <int EPI>
; __device__ __forceinline__ void gemm_phase(char* shm, const u16* A, const u16* Bt, int K, int nM, int nN, u16* Cb, float* X,
;                            int ldc, const u16* G, float* SQ, int bid, int nb) {
;     ...
; #pragma unroll
;       for (int q = 0; q < 8; ++q) rs[q] = ((const float*)(shm + LDS_RST))[(q >> 2) * 128 + wr * 64 + (q & 3) * 16 + fr];
;     }
; #pragma unroll
;     for (int ai = 0; ai < 2; ++ai)
; #pragma unroll
;       for (int bj = 0; bj < 2; ++bj)
; #pragma unroll
;         for (int m = 0; m < 4; ++m) {
;           const long row = brow + ai * 128 + wr * 64 + m * 16 + fr;
;           const int col = bcol + bj * 128 + wc * 32 + fq * 8;
;           float c[8];
; #pragma unroll
;           for (int j = 0; j < 4; ++j) { c[j] = acc[ai][bj][m][0][j]; c[4 + j] = acc[ai][bj][m][1][j]; }
;           if (EPI == EPI_BF16) {
;             const float r1 = rs[ai * 4 + m];
;             u16x8 o;
; #pragma unroll
;             for (int j = 0; j < 8; ++j) o[j] = f2bf(c[j] * r1);
;             *(u16x8*)(Cb + row * ldc + col) = o;
	v_alignbit_b32 v71, v0, v71, 16
	v_alignbit_b32 v72, v66, v0, 16
	v_mul_f32_e32 v0, v69, v137
	v_cvt_pk_bf16_f32 v0, v0, s0
	v_mul_f32_e32 v62, v62, v132
	v_alignbit_b32 v73, v0, v66, 16
	v_cvt_pk_bf16_f32 v66, v62, s0
	v_mov_b32_e32 v62, v63
	v_mov_b32_e32 v63, v64
	v_pk_mov_b32 v[64:65], v[64:65], v[58:59] op_sel:[1,0]
	v_mov_b32_e32 v58, v59
	v_mov_b32_e32 v59, v60
	v_pk_mul_f32 v[58:59], v[58:59], v[132:133] op_sel_hi:[1,0]
	v_pk_mul_f32 v[62:63], v[62:63], v[132:133] op_sel_hi:[1,0]
	v_pk_mul_f32 v[64:65], v[64:65], v[132:133] op_sel_hi:[1,0]
	v_cvt_pk_bf16_f32 v58, v58, v59
	v_mul_f32_e32 v59, v61, v132
	v_add_u32_e32 v0, 0x80, v140
	v_cvt_pk_bf16_f32 v63, v62, v63
	v_cvt_pk_bf16_f32 v64, v64, v65
	v_cvt_pk_bf16_f32 v59, v59, s0
	v_perm_b32 v62, v63, v66, s74
	v_alignbit_b32 v63, v64, v63, 16
	v_alignbit_b32 v64, v58, v64, 16
	v_alignbit_b32 v65, v59, v58, 16
	v_mad_i64_i32 v[58:59], s[4:5], v0, s66, v[134:135]
	v_mul_f32_e32 v0, v54, v133
	v_cvt_pk_bf16_f32 v61, v0, s0
	v_mov_b32_e32 v54, v55
	v_mov_b32_e32 v55, v56
	v_mov_b32_e32 v0, v133
	v_pk_mov_b32 v[56:57], v[56:57], v[50:51] op_sel:[1,0]
	v_mov_b32_e32 v50, v51
	v_mov_b32_e32 v51, v52
	v_pk_mul_f32 v[50:51], v[50:51], v[0:1] op_sel_hi:[1,0]
	v_mul_f32_e32 v46, v46, v130
	v_cvt_pk_bf16_f32 v50, v50, v51
	v_mul_f32_e32 v51, v53, v133
	v_cvt_pk_bf16_f32 v53, v46, s0
	v_mov_b32_e32 v46, v47
	v_mov_b32_e32 v47, v48
	v_pk_mov_b32 v[48:49], v[48:49], v[42:43] op_sel:[1,0]
	v_mov_b32_e32 v42, v43
	v_mov_b32_e32 v43, v44
	v_pk_mul_f32 v[42:43], v[42:43], v[130:131] op_sel_hi:[1,0]
	v_pk_mul_f32 v[46:47], v[46:47], v[130:131] op_sel_hi:[1,0]
	v_pk_mul_f32 v[48:49], v[48:49], v[130:131] op_sel_hi:[1,0]
	v_cvt_pk_bf16_f32 v42, v42, v43
	v_mul_f32_e32 v43, v45, v130
	v_add_u32_e32 v52, 0xa0, v140
	v_cvt_pk_bf16_f32 v47, v46, v47
	v_cvt_pk_bf16_f32 v48, v48, v49
	v_cvt_pk_bf16_f32 v43, v43, s0
	v_perm_b32 v46, v47, v53, s74
	v_alignbit_b32 v47, v48, v47, 16
	v_alignbit_b32 v48, v42, v48, 16
	v_alignbit_b32 v49, v43, v42, 16
	v_mad_i64_i32 v[42:43], s[4:5], v52, s66, v[134:135]
	v_mul_f32_e32 v38, v38, v131
	v_mul_f32_e32 v30, v30, v132
	global_store_dwordx4 v[42:43], v[46:49], off nt
	v_mul_f32_e32 v22, v22, v133
	v_pk_mul_f32 v[54:55], v[54:55], v[0:1] op_sel_hi:[1,0]
	v_cvt_pk_bf16_f32 v46, v38, s0
	v_mov_b32_e32 v38, v39
	v_mov_b32_e32 v39, v40
	v_pk_mov_b32 v[40:41], v[40:41], v[34:35] op_sel:[1,0]
	v_mov_b32_e32 v34, v35
	v_mov_b32_e32 v35, v36
	v_cvt_pk_bf16_f32 v36, v30, s0
	v_mov_b32_e32 v30, v31
	v_mov_b32_e32 v31, v32
	v_pk_mov_b32 v[32:33], v[32:33], v[26:27] op_sel:[1,0]
	v_mov_b32_e32 v26, v27
	v_mov_b32_e32 v27, v28
	v_pk_mul_f32 v[26:27], v[26:27], v[132:133] op_sel_hi:[1,0]
	v_pk_mul_f32 v[30:31], v[30:31], v[132:133] op_sel_hi:[1,0]
	v_pk_mul_f32 v[32:33], v[32:33], v[132:133] op_sel_hi:[1,0]
	v_cvt_pk_bf16_f32 v26, v26, v27
	v_mul_f32_e32 v27, v29, v132
	v_cvt_pk_bf16_f32 v31, v30, v31
	v_cvt_pk_bf16_f32 v32, v32, v33
	v_cvt_pk_bf16_f32 v27, v27, s0
	v_perm_b32 v30, v31, v36, s74
	v_alignbit_b32 v31, v32, v31, 16
	v_alignbit_b32 v32, v26, v32, 16
	v_alignbit_b32 v33, v27, v26, 16
	v_cvt_pk_bf16_f32 v26, v22, s0
	v_mov_b32_e32 v22, v23
	v_mov_b32_e32 v23, v24
	v_pk_mov_b32 v[24:25], v[24:25], v[18:19] op_sel:[1,0]
	v_mov_b32_e32 v18, v19
	v_mov_b32_e32 v19, v20
	v_pk_mul_f32 v[18:19], v[18:19], v[0:1] op_sel_hi:[1,0]
	v_pk_mul_f32 v[56:57], v[56:57], v[0:1] op_sel_hi:[1,0]
	v_pk_mul_f32 v[22:23], v[22:23], v[0:1] op_sel_hi:[1,0]
	v_pk_mul_f32 v[24:25], v[24:25], v[0:1] op_sel_hi:[1,0]
	v_cvt_pk_bf16_f32 v0, v18, v19
	v_mul_f32_e32 v18, v21, v133
	v_cvt_pk_bf16_f32 v23, v22, v23
	v_cvt_pk_bf16_f32 v24, v24, v25
	v_cvt_pk_bf16_f32 v18, v18, s0
	v_perm_b32 v22, v23, v26, s74
	v_alignbit_b32 v23, v24, v23, 16
	v_alignbit_b32 v24, v0, v24, 16
	v_alignbit_b32 v25, v18, v0, 16
	v_mul_f32_e32 v0, v14, v130
	v_mov_b32_e32 v14, v15
	v_mov_b32_e32 v15, v16
; template <int EPI>
; __device__ __forceinline__ void gemm_phase(char* shm, const u16* A, const u16* Bt, int K, int nM, int nN, u16* Cb, float* X,
;                            int ldc, const u16* G, float* SQ, int bid, int nb) {
;     ...
; #pragma unroll
;       for (int q = 0; q < 8; ++q) rs[q] = ((const float*)(shm + LDS_RST))[(q >> 2) * 128 + wr * 64 + (q & 3) * 16 + fr];
;     }
; #pragma unroll
;     for (int ai = 0; ai < 2; ++ai)
; #pragma unroll
;       for (int bj = 0; bj < 2; ++bj)
; #pragma unroll
;         for (int m = 0; m < 4; ++m) {
;           const long row = brow + ai * 128 + wr * 64 + m * 16 + fr;
;           const int col = bcol + bj * 128 + wc * 32 + fq * 8;
;           float c[8];
; #pragma unroll
;           for (int j = 0; j < 4; ++j) { c[j] = acc[ai][bj][m][0][j]; c[4 + j] = acc[ai][bj][m][1][j]; }
;           if (EPI == EPI_BF16) {
;             const float r1 = rs[ai * 4 + m];
;             u16x8 o;
; #pragma unroll
;             for (int j = 0; j < 8; ++j) o[j] = f2bf(c[j] * r1);
;             *(u16x8*)(Cb + row * ldc + col) = o;
	v_pk_mul_f32 v[14:15], v[14:15], v[130:131] op_sel_hi:[1,0]
	v_pk_mov_b32 v[16:17], v[16:17], v[10:11] op_sel:[1,0]
	v_mov_b32_e32 v10, v11
	v_mov_b32_e32 v11, v12
	v_cvt_pk_bf16_f32 v0, v0, s0
	v_cvt_pk_bf16_f32 v15, v14, v15
	v_pk_mul_f32 v[16:17], v[16:17], v[130:131] op_sel_hi:[1,0]
	v_pk_mul_f32 v[10:11], v[10:11], v[130:131] op_sel_hi:[1,0]
	v_perm_b32 v14, v15, v0, s74
	v_cvt_pk_bf16_f32 v0, v16, v17
	v_cvt_pk_bf16_f32 v10, v10, v11
	v_alignbit_b32 v15, v0, v15, 16
	v_alignbit_b32 v16, v10, v0, 16
	v_mul_f32_e32 v0, v13, v130
	v_cvt_pk_bf16_f32 v0, v0, s0
	v_add_u32_e32 v45, 0xb0, v140
	v_mov_b32_e32 v44, v131
	v_alignbit_b32 v17, v0, v10, 16
	v_mul_f32_e32 v0, v6, v131
	v_mov_b32_e32 v6, v7
	v_mov_b32_e32 v7, v8
	v_pk_mul_f32 v[6:7], v[6:7], v[44:45] op_sel_hi:[1,0]
	v_pk_mov_b32 v[8:9], v[8:9], v[2:3] op_sel:[1,0]
	v_mov_b32_e32 v2, v3
	v_mov_b32_e32 v3, v4
	v_cvt_pk_bf16_f32 v0, v0, s0
	v_cvt_pk_bf16_f32 v7, v6, v7
	v_pk_mul_f32 v[8:9], v[8:9], v[44:45] op_sel_hi:[1,0]
	v_pk_mul_f32 v[2:3], v[2:3], v[44:45] op_sel_hi:[1,0]
	v_pk_mul_f32 v[98:99], v[98:99], v[108:109] op_sel_hi:[1,0]
	v_pk_mul_f32 v[34:35], v[34:35], v[44:45] op_sel_hi:[1,0]
	v_perm_b32 v6, v7, v0, s74
	v_cvt_pk_bf16_f32 v0, v8, v9
	v_cvt_pk_bf16_f32 v2, v2, v3
	v_pk_mul_f32 v[102:103], v[102:103], v[108:109] op_sel_hi:[1,0]
	v_pk_mul_f32 v[104:105], v[104:105], v[108:109] op_sel_hi:[1,0]
	v_cvt_pk_bf16_f32 v98, v98, v99
	v_mul_f32_e32 v99, v101, v137
	v_pk_mul_f32 v[38:39], v[38:39], v[44:45] op_sel_hi:[1,0]
	v_pk_mul_f32 v[40:41], v[40:41], v[44:45] op_sel_hi:[1,0]
	v_cvt_pk_bf16_f32 v34, v34, v35
	v_mul_f32_e32 v35, v37, v131
	v_alignbit_b32 v7, v0, v7, 16
	v_alignbit_b32 v8, v2, v0, 16
	v_mul_f32_e32 v0, v5, v131
	v_or_b32_e32 v124, 16, v140
	v_cvt_pk_bf16_f32 v119, v118, v119
	v_cvt_pk_bf16_f32 v120, v120, v121
	v_cvt_pk_bf16_f32 v115, v115, s0
	v_cvt_pk_bf16_f32 v103, v102, v103
	v_cvt_pk_bf16_f32 v104, v104, v105
	v_cvt_pk_bf16_f32 v99, v99, s0
	v_add_u32_e32 v60, 0x90, v140
	v_cvt_pk_bf16_f32 v55, v54, v55
	v_cvt_pk_bf16_f32 v56, v56, v57
	v_cvt_pk_bf16_f32 v51, v51, s0
	v_cvt_pk_bf16_f32 v39, v38, v39
	v_cvt_pk_bf16_f32 v40, v40, v41
	v_cvt_pk_bf16_f32 v35, v35, s0
	v_cvt_pk_bf16_f32 v0, v0, s0
	v_mad_i64_i32 v[122:123], s[4:5], v140, s66, v[134:135]
	v_perm_b32 v118, v119, v125, s74
	v_alignbit_b32 v119, v120, v119, 16
	v_alignbit_b32 v120, v114, v120, 16
	v_alignbit_b32 v121, v115, v114, 16
	v_mad_i64_i32 v[114:115], s[4:5], v124, s66, v[134:135]
	v_perm_b32 v102, v103, v110, s74
	v_alignbit_b32 v103, v104, v103, 16
	v_alignbit_b32 v104, v98, v104, 16
	v_alignbit_b32 v105, v99, v98, 16
	v_mad_i64_i32 v[98:99], s[4:5], v109, s66, v[134:135]
	v_perm_b32 v54, v55, v61, s74
	v_alignbit_b32 v55, v56, v55, 16
	v_alignbit_b32 v56, v50, v56, 16
	v_alignbit_b32 v57, v51, v50, 16
	v_mad_i64_i32 v[50:51], s[4:5], v60, s66, v[134:135]
	v_perm_b32 v38, v39, v46, s74
	v_alignbit_b32 v39, v40, v39, 16
	v_alignbit_b32 v40, v34, v40, 16
	v_alignbit_b32 v41, v35, v34, 16
	v_mad_i64_i32 v[34:35], s[4:5], v45, s66, v[134:135]
	v_alignbit_b32 v9, v0, v2, 16
	s_mov_b64 s[6:7], -1
	s_and_b64 vcc, exec, s[8:9]
	global_store_dwordx4 v[122:123], v[126:129], off nt
	global_store_dwordx4 v[114:115], v[118:121], off nt
	global_store_dwordx4 v[98:99], v[102:105], off nt
	global_store_dwordx4 v[122:123], v[94:97], off offset:256 nt
	global_store_dwordx4 v[114:115], v[86:89], off offset:256 nt
	global_store_dwordx4 v[106:107], v[78:81], off offset:256 nt
	global_store_dwordx4 v[98:99], v[70:73], off offset:256 nt
	global_store_dwordx4 v[58:59], v[62:65], off nt
	global_store_dwordx4 v[50:51], v[54:57], off nt
	global_store_dwordx4 v[34:35], v[38:41], off nt
	global_store_dwordx4 v[58:59], v[30:33], off offset:256 nt
	global_store_dwordx4 v[50:51], v[22:25], off offset:256 nt
	global_store_dwordx4 v[42:43], v[14:17], off offset:256 nt
	global_store_dwordx4 v[34:35], v[6:9], off offset:256 nt
	s_cbranch_vccnz .LBB0_406
